# phase 14 (K-row norm+rope): touch the next row's cache lines after the current row's loads return (3 serial HBM round trips per row become cache hits)
# baseline (speedup 1.0000x reference)
; #define KIN(i) (((const float* const __attribute__((address_space(4)))*)kp)[i])
; template <int LO, int HI>
; DEV void run_phases(LAS unsigned char* lds, const int ph_lo, const int ph_hi, const int G, const int wave0, unsigned& nbar) {
;     ...
;             for (int it = TX + gw; it < TX + TT; it += NGW) {
;                 const bool isq = it < TX; const int row = isq ? it : it - TX;
;                 const bf16_t* bsrc = isq ? BF(WS_QB) + (size_t)row * 1536 + h * 96 : BF(WS_KRAW) + (size_t)row * 1024 + h * 64;
;                 const float* kper = FP(WS_KPE) + (size_t)row * 32;
;                 const float* gn = isq ? KIN(I_MQN) : KIN(I_MKN);
;                 float v[3][8]; float ss = 0.f;
; #pragma unroll
;                 for (int j = 0; j < 3; ++j) { const int d0 = 8 * (3 * q + j); const bool frombf = isq || d0 < 64;
;                     const int db = frombf ? d0 : 0, dk = frombf ? 0 : d0 - 64;
;                     const u32x4 raw = *(const u32x4*)(bsrc + db); const f32x4 t0 = *(const f32x4*)(kper + dk), t1 = *(const f32x4*)(kper + dk + 4);
;                     v[j][0] = frombf ? __uint_as_float(raw.x << 16) : t0[0]; v[j][1] = frombf ? __uint_as_float(raw.x & 0xffff0000u) : t0[1];
;                     v[j][2] = frombf ? __uint_as_float(raw.y << 16) : t0[2]; v[j][3] = frombf ? __uint_as_float(raw.y & 0xffff0000u) : t0[3];
;                     v[j][4] = frombf ? __uint_as_float(raw.z << 16) : t1[0]; v[j][5] = frombf ? __uint_as_float(raw.z & 0xffff0000u) : t1[1];
;                     v[j][6] = frombf ? __uint_as_float(raw.w << 16) : t1[2]; v[j][7] = frombf ? __uint_as_float(raw.w & 0xffff0000u) : t1[3];
; #pragma unroll
;                     for (int e = 0; e < 8; ++e) ss += v[j][e] * v[j][e]; }
;                 ss += __shfl_xor(ss, 1); ss += __shfl_xor(ss, 2);
;                 const float rstd = 1.0f / sqrtf(ss * (1.f / 96.f) + EPS);
; #pragma unroll
;                 for (int j = 0; j < 3; ++j) { const int d0 = 8 * (3 * q + j); const f32x4 g0 = *(const f32x4*)(gn + d0), g1 = *(const f32x4*)(gn + d0 + 4);
; #pragma unroll
;                     for (int e = 0; e < 4; ++e) { v[j][e] *= rstd * g0[e]; v[j][4 + e] *= rstd * g1[e]; } }
.LBB0_2153:
	s_and_b64 s[12:13], exec, s[10:11]
	s_cselect_b32 s16, s1, s14
	s_ashr_i32 s17, s16, 31
	s_lshl_b64 s[12:13], s[16:17], 7
	v_readlane_b32 s20, v251, 37
	v_readlane_b32 s21, v251, 38
	s_add_u32 s12, s20, s12
	s_addc_u32 s13, s21, s13
	v_readlane_b32 s20, v251, 31
	v_readlane_b32 s21, v251, 32
	s_add_u32 s18, s20, s18
	s_addc_u32 s19, s21, s19
	s_or_b64 vcc, s[6:7], s[10:11]
	v_cndmask_b32_e32 v2, 0, v10, vcc
	v_lshlrev_b32_e32 v96, 1, v2
	v_lshl_add_u64 v[2:3], v[0:1], 0, v[96:97]
	v_cndmask_b32_e64 v96, 32, 0, vcc
	global_load_dwordx4 v[24:27], v[2:3], off
	v_lshl_add_u64 v[2:3], s[12:13], 0, v[96:97]
	s_load_dwordx2 s[18:19], s[18:19], 0x0
	global_load_dwordx4 v[28:31], v[2:3], off offset:16
	global_load_dwordx4 v[32:35], v[2:3], off
	v_cndmask_b32_e32 v17, 0, v12, vcc
	v_lshlrev_b32_e32 v96, 1, v17
	v_lshlrev_b32_e32 v64, 2, v10
	s_waitcnt vmcnt(2)
	v_lshlrev_b32_e32 v2, 16, v24
	v_lshlrev_b32_e32 v6, 16, v26
	s_waitcnt vmcnt(0)
	v_cndmask_b32_e32 v5, v32, v2, vcc
	v_and_b32_e32 v2, 0xffff0000, v24
	v_cndmask_b32_e32 v24, v28, v6, vcc
	v_and_b32_e32 v6, 0xffff0000, v26
	v_cndmask_b32_e32 v4, v33, v2, vcc
	v_lshlrev_b32_e32 v2, 16, v25
	v_cndmask_b32_e32 v22, v29, v6, vcc
	v_lshlrev_b32_e32 v6, 16, v27
	v_cndmask_b32_e32 v3, v34, v2, vcc
	v_and_b32_e32 v2, 0xffff0000, v25
	v_cndmask_b32_e32 v7, v30, v6, vcc
	v_and_b32_e32 v6, 0xffff0000, v27
	v_lshl_add_u64 v[26:27], v[0:1], 0, v[96:97]
	v_cndmask_b32_e64 v96, 64, 0, vcc
	v_cndmask_b32_e32 v2, v35, v2, vcc
	global_load_dwordx4 v[26:29], v[26:27], off
	v_lshl_add_u64 v[34:35], s[12:13], 0, v[96:97]
	v_cndmask_b32_e32 v6, v31, v6, vcc
	global_load_dwordx4 v[30:33], v[34:35], off offset:16
	s_nop 0
	global_load_dwordx4 v[34:37], v[34:35], off
	v_mul_f32_e32 v40, v4, v4
	v_fmac_f32_e32 v40, v5, v5
	v_fmac_f32_e32 v40, v3, v3
	v_fmac_f32_e32 v40, v2, v2
	v_fmac_f32_e32 v40, v24, v24
	v_fmac_f32_e32 v40, v22, v22
	v_fmac_f32_e32 v40, v7, v7
	v_fmac_f32_e32 v40, v6, v6
	s_waitcnt vmcnt(2)
	v_lshlrev_b32_e32 v17, 16, v26
	s_waitcnt vmcnt(0)
	v_cndmask_b32_e32 v44, v34, v17, vcc
	v_and_b32_e32 v17, 0xffff0000, v26
	v_cndmask_b32_e32 v45, v35, v17, vcc
	v_lshlrev_b32_e32 v17, 16, v27
	v_cndmask_b32_e32 v47, v36, v17, vcc
	v_and_b32_e32 v17, 0xffff0000, v27
	v_cndmask_b32_e32 v49, v37, v17, vcc
	v_lshlrev_b32_e32 v17, 16, v28
	v_cndmask_b32_e32 v51, v30, v17, vcc
	v_and_b32_e32 v17, 0xffff0000, v28
	v_cndmask_b32_e32 v53, v31, v17, vcc
	v_lshlrev_b32_e32 v17, 16, v29
	v_cndmask_b32_e32 v62, v32, v17, vcc
	v_and_b32_e32 v17, 0xffff0000, v29
	v_cndmask_b32_e32 v63, v33, v17, vcc
	s_or_b64 vcc, s[8:9], s[10:11]
	v_cndmask_b32_e32 v17, 0, v14, vcc
	v_lshlrev_b32_e32 v96, 1, v17
	v_lshl_add_u64 v[0:1], v[0:1], 0, v[96:97]
	global_load_dwordx4 v[32:35], v[0:1], off
	v_cndmask_b32_e64 v1, v11, 0, vcc
	v_cndmask_b32_e64 v0, v16, 0, vcc
	v_lshl_add_u64 v[0:1], v[0:1], 2, s[12:13]
	global_load_dwordx4 v[36:39], v[0:1], off offset:16
	global_load_dwordx4 v[26:29], v[0:1], off
	v_fmac_f32_e32 v40, v44, v44
	v_fmac_f32_e32 v40, v45, v45
	v_fmac_f32_e32 v40, v47, v47
	v_fmac_f32_e32 v40, v49, v49
	v_fmac_f32_e32 v40, v51, v51
	v_fmac_f32_e32 v40, v53, v53
	v_fmac_f32_e32 v40, v62, v62
	v_fmac_f32_e32 v40, v63, v63
	s_cmpk_gt_i32 s16, 0x7fff
	s_waitcnt vmcnt(2)
	v_lshlrev_b32_e32 v0, 16, v32
	s_waitcnt vmcnt(0)
	v_cndmask_b32_e32 v25, v26, v0, vcc
	v_and_b32_e32 v0, 0xffff0000, v32
	v_cndmask_b32_e32 v23, v27, v0, vcc
	v_lshlrev_b32_e32 v0, 16, v33
	v_fmac_f32_e32 v40, v25, v25
	v_cndmask_b32_e32 v21, v28, v0, vcc
	v_and_b32_e32 v0, 0xffff0000, v33
	v_fmac_f32_e32 v40, v23, v23
	v_cndmask_b32_e32 v17, v29, v0, vcc
	v_lshlrev_b32_e32 v0, 16, v34
	v_fmac_f32_e32 v40, v21, v21
	v_cndmask_b32_e32 v33, v36, v0, vcc
	v_and_b32_e32 v0, 0xffff0000, v34
	v_fmac_f32_e32 v40, v17, v17
	v_cndmask_b32_e32 v31, v37, v0, vcc
	v_lshlrev_b32_e32 v0, 16, v35
	v_fmac_f32_e32 v40, v33, v33
	v_cndmask_b32_e32 v29, v38, v0, vcc
	v_and_b32_e32 v0, 0xffff0000, v35
	v_fmac_f32_e32 v40, v31, v31
	v_cndmask_b32_e32 v27, v39, v0, vcc
	v_fmac_f32_e32 v40, v29, v29
	v_fmac_f32_e32 v40, v27, v27
	ds_bpermute_b32 v0, v13, v40
	s_waitcnt lgkmcnt(0)
	v_add_f32_e32 v0, v40, v0
	global_load_dwordx4 v[54:57], v64, s[18:19] offset:48
	global_load_dwordx4 v[58:61], v64, s[18:19] offset:32
	global_load_dwordx4 v[36:39], v64, s[18:19] offset:16
	global_load_dwordx4 v[40:43], v64, s[18:19]
	ds_bpermute_b32 v1, v15, v0
	s_waitcnt lgkmcnt(0)
	v_add_f32_e32 v0, v0, v1
	v_fmamk_f32 v0, v0, 0x3c2aaaab, v180
	v_cmp_gt_f32_e32 vcc, s78, v0
	v_mul_f32_e32 v1, 0x4f800000, v0
	s_nop 0
	v_cndmask_b32_e32 v0, v0, v1, vcc
	v_sqrt_f32_e32 v1, v0
	s_nop 0
	v_add_u32_e32 v26, -1, v1
	v_fma_f32 v28, -v26, v1, v0
	v_cmp_ge_f32_e64 s[12:13], 0, v28
	v_add_u32_e32 v28, 1, v1
	s_nop 0
	v_cndmask_b32_e64 v26, v1, v26, s[12:13]
	v_fma_f32 v1, -v28, v1, v0
	v_cmp_lt_f32_e64 s[12:13], 0, v1
	s_nop 1
	v_cndmask_b32_e64 v1, v26, v28, s[12:13]
	v_mul_f32_e32 v26, 0x37800000, v1
	v_cndmask_b32_e32 v1, v1, v26, vcc
	v_cmp_class_f32_e32 vcc, v0, v181
	s_nop 1
	v_cndmask_b32_e32 v0, v1, v0, vcc
	v_div_scale_f32 v1, s[12:13], v0, v0, 1.0
	v_rcp_f32_e32 v26, v1
	s_nop 0
	v_fma_f32 v28, -v1, v26, 1.0
	v_fmac_f32_e32 v26, v28, v26
	v_div_scale_f32 v28, vcc, 1.0, v0, 1.0
	v_mul_f32_e32 v30, v28, v26
	v_fma_f32 v32, -v1, v30, v28
	v_fmac_f32_e32 v30, v32, v26
	v_fma_f32 v1, -v1, v30, v28
	v_div_fmas_f32 v1, v1, v26, v30
	v_div_fixup_f32 v35, v1, v0, 1.0
	s_waitcnt vmcnt(0)
	v_mul_f32_e32 v0, v40, v35
	v_mul_f32_e32 v40, v5, v0
	v_mul_f32_e32 v0, v36, v35
	v_mul_f32_e32 v30, v24, v0
	v_mul_f32_e32 v0, v41, v35
	v_mul_f32_e32 v46, v4, v0
	v_mul_f32_e32 v0, v37, v35
	v_mul_f32_e32 v36, v22, v0
	v_mul_f32_e32 v0, v42, v35
	v_mul_f32_e32 v50, v3, v0
	v_mul_f32_e32 v0, v38, v35
	v_mul_f32_e32 v42, v7, v0
	v_mul_f32_e32 v0, v43, v35
	v_mul_f32_e32 v52, v2, v0
	v_mul_f32_e32 v0, v39, v35
	v_mul_f32_e32 v48, v6, v0
	v_mul_f32_e32 v0, v58, v35
	v_mul_f32_e32 v26, v44, v0
	v_mul_f32_e32 v0, v54, v35
	v_mul_f32_e32 v22, v51, v0
	v_mul_f32_e32 v0, v59, v35
	v_mul_f32_e32 v32, v45, v0
	v_mul_f32_e32 v0, v55, v35
	v_mul_f32_e32 v24, v53, v0
	v_mul_f32_e32 v0, v60, v35
	v_mul_f32_e32 v38, v47, v0
	v_mul_f32_e32 v0, v56, v35
	v_mul_f32_e32 v28, v62, v0
	v_mul_f32_e32 v0, v61, v35
	v_mul_f32_e32 v44, v49, v0
	v_mul_f32_e32 v0, v57, v35
	v_mul_f32_e32 v34, v63, v0
	global_load_dwordx4 v[0:3], v64, s[18:19] offset:80
	global_load_dwordx4 v[4:7], v64, s[18:19] offset:64
	s_waitcnt vmcnt(1)
	v_mul_f32_e32 v0, v0, v35
	s_waitcnt vmcnt(0)
	s_add_i32 s12, s14, s84
	s_cmp_lt_i32 s12, 0x8800
	s_cbranch_scc0 .Lp14_nopf
	s_mov_b32 s13, 0
	s_lshl_b64 s[18:19], s[12:13], 11
	v_lshl_add_u64 v[98:99], v[8:9], 0, s[18:19]
	global_load_dwordx4 v[100:103], v[98:99], off
	global_load_dwordx4 v[100:103], v[98:99], off offset:64
	s_lshl_b64 s[18:19], s[12:13], 7
	v_readlane_b32 s12, v251, 37
	v_readlane_b32 s13, v251, 38
	s_add_u32 s12, s12, s18
	s_addc_u32 s13, s13, s19
	global_load_dword v100, v97, s[12:13]
	global_load_dword v100, v97, s[12:13] offset:64
; template <int LO, int HI>
; DEV void run_phases(LAS unsigned char* lds, const int ph_lo, const int ph_hi, const int G, const int wave0, unsigned& nbar) {
;     ...
;                 for (int j = 0; j < 3; ++j) { const int d0 = 8 * (3 * q + j); const f32x4 g0 = *(const f32x4*)(gn + d0), g1 = *(const f32x4*)(gn + d0 + 4);
; #pragma unroll
;                     for (int e = 0; e < 4; ++e) { v[j][e] *= rstd * g0[e]; v[j][4 + e] *= rstd * g1[e]; } }
;                 if (row < TX) { const int t = row & 4095; const float pr = (float)(t >> 6), pc = (float)(t & 63);
; #pragma unroll
;                     for (int e = 0; e < 8; ++e) { const float invf = exp2f(-(float)e * (13.287712379549449f / 8.f));
;                         const float rr_ = pr * invf * 0.15915494309189535f, rc_ = pc * invf * 0.15915494309189535f;
;                         const float sr = __builtin_amdgcn_sinf(rr_), cr = __builtin_amdgcn_cosf(rr_), sc_ = __builtin_amdgcn_sinf(rc_), cc = __builtin_amdgcn_cosf(rc_);
;                         const float send = (q == 2) ? v[2][e] : v[0][e]; const float recv = __shfl_xor(send, 1);
;                         if (q == 2) v[2][e] = v[2][e] * cr - recv * sr;
;                         if (q == 3) { v[0][e] = recv * sr + v[0][e] * cr; const float b1 = v[1][e], b2 = v[2][e]; v[1][e] = b1 * cc - b2 * sc_; v[2][e] = b1 * sc_ + b2 * cc; } } }
.Lp14_nopf:
	s_cmpk_gt_i32 s16, 0x7fff
	v_mul_f32_e32 v4, v4, v35
	v_mul_f32_e32 v5, v5, v35
	v_mul_f32_e32 v1, v1, v35
	v_mul_f32_e32 v6, v6, v35
	v_mul_f32_e32 v2, v2, v35
	v_mul_f32_e32 v7, v7, v35
	v_mul_f32_e32 v3, v3, v35
	v_mul_f32_e32 v4, v25, v4
	v_mul_f32_e32 v0, v33, v0
	v_mul_f32_e32 v5, v23, v5
	v_mul_f32_e32 v1, v31, v1
	v_mul_f32_e32 v6, v21, v6
	v_mul_f32_e32 v2, v29, v2
	v_mul_f32_e32 v7, v17, v7
	v_mul_f32_e32 v3, v27, v3
	s_cbranch_scc1 .LBB0_2150
	s_bfe_u32 s1, s16, 0x60006
	v_cvt_f32_ubyte0_e32 v17, s1
	v_cndmask_b32_e64 v25, v40, v4, s[2:3]
	v_mul_f32_e32 v23, 0.15915494, v17
	ds_bpermute_b32 v41, v13, v25
	s_and_b32 s1, s16, 63
	v_sin_f32_e32 v55, v23
	v_cos_f32_e32 v54, v23
	v_cvt_f32_ubyte0_e32 v21, s1
	v_mul_f32_e32 v23, 0.15915494, v21
	v_sin_f32_e32 v57, v23
	v_cos_f32_e32 v56, v23
	s_waitcnt lgkmcnt(0)
	v_pk_mul_f32 v[58:59], v[54:55], v[40:41]
	s_nop 0
	v_fma_f32 v23, v54, v4, -v59
	v_cndmask_b32_e64 v27, v4, v23, s[2:3]
	v_pk_mul_f32 v[54:55], v[56:57], v[26:27]
	v_add_f32_e32 v4, v58, v59
	v_sub_f32_e32 v23, v54, v55
	v_mov_b32_e32 v54, v57
	v_mov_b32_e32 v55, v56
	v_pk_mul_f32 v[54:55], v[54:55], v[26:27]
	v_cndmask_b32_e64 v40, v40, v4, s[4:5]
	v_add_f32_e32 v25, v54, v55
	v_cndmask_b32_e64 v4, v27, v25, s[4:5]
	v_cndmask_b32_e64 v26, v26, v23, s[4:5]
	v_mul_f32_e32 v23, 0x3ea1e89b, v17
	v_cndmask_b32_e64 v27, v46, v5, s[2:3]
	v_mul_f32_e32 v23, 0.15915494, v23
	ds_bpermute_b32 v47, v13, v27
	v_sin_f32_e32 v55, v23
	v_cos_f32_e32 v54, v23
	v_mul_f32_e32 v25, 0x3ea1e89b, v21
	v_mul_f32_e32 v23, 0.15915494, v25
	v_sin_f32_e32 v57, v23
	v_cos_f32_e32 v56, v23
	s_waitcnt lgkmcnt(0)
	v_pk_mul_f32 v[58:59], v[54:55], v[46:47]
	v_cndmask_b32_e64 v27, v50, v6, s[2:3]
	v_fma_f32 v23, v54, v5, -v59
	v_cndmask_b32_e64 v33, v5, v23, s[2:3]
	v_pk_mul_f32 v[54:55], v[56:57], v[32:33]
	ds_bpermute_b32 v51, v13, v27
	v_sub_f32_e32 v23, v54, v55
	v_mov_b32_e32 v54, v57
	v_mov_b32_e32 v55, v56
	v_pk_mul_f32 v[54:55], v[54:55], v[32:33]
	v_cndmask_b32_e64 v32, v32, v23, s[4:5]
	v_mul_f32_e32 v23, 0x3dcccccd, v17
	v_mul_f32_e32 v23, 0.15915494, v23
	v_add_f32_e32 v5, v58, v59
	v_add_f32_e32 v25, v54, v55
	v_sin_f32_e32 v55, v23
	v_cos_f32_e32 v54, v23
	v_cndmask_b32_e64 v46, v46, v5, s[4:5]
	v_cndmask_b32_e64 v5, v33, v25, s[4:5]
	v_mul_f32_e32 v25, 0x3dcccccd, v21
	v_mul_f32_e32 v23, 0.15915494, v25
	v_sin_f32_e32 v57, v23
	v_cos_f32_e32 v56, v23
	s_waitcnt lgkmcnt(0)
	v_pk_mul_f32 v[58:59], v[54:55], v[50:51]
	v_cndmask_b32_e64 v27, v52, v7, s[2:3]
	v_fma_f32 v23, v54, v6, -v59
	v_cndmask_b32_e64 v39, v6, v23, s[2:3]
	v_pk_mul_f32 v[54:55], v[56:57], v[38:39]
	ds_bpermute_b32 v53, v13, v27
	v_sub_f32_e32 v23, v54, v55
	v_mov_b32_e32 v54, v57
	v_mov_b32_e32 v55, v56
	v_pk_mul_f32 v[54:55], v[54:55], v[38:39]
	v_cndmask_b32_e64 v38, v38, v23, s[4:5]
	v_mul_f32_e32 v23, 0x3d0186e3, v17
	v_mul_f32_e32 v23, 0.15915494, v23
	v_add_f32_e32 v6, v58, v59
	v_add_f32_e32 v25, v54, v55
	v_sin_f32_e32 v55, v23
	v_cos_f32_e32 v54, v23
	v_cndmask_b32_e64 v50, v50, v6, s[4:5]
	v_cndmask_b32_e64 v6, v39, v25, s[4:5]
	v_mul_f32_e32 v25, 0x3d0186e3, v21
	v_mul_f32_e32 v23, 0.15915494, v25
	v_sin_f32_e32 v57, v23
	v_cos_f32_e32 v56, v23
	s_waitcnt lgkmcnt(0)
	v_pk_mul_f32 v[58:59], v[54:55], v[52:53]
	v_cndmask_b32_e64 v27, v30, v0, s[2:3]
	v_fma_f32 v23, v54, v7, -v59
	v_cndmask_b32_e64 v45, v7, v23, s[2:3]
	v_pk_mul_f32 v[54:55], v[56:57], v[44:45]
	ds_bpermute_b32 v31, v13, v27
	v_sub_f32_e32 v23, v54, v55
	v_mov_b32_e32 v54, v57
	v_mov_b32_e32 v55, v56
	v_pk_mul_f32 v[54:55], v[54:55], v[44:45]
	v_cndmask_b32_e64 v44, v44, v23, s[4:5]
	v_mul_f32_e32 v23, 0x3c23d70b, v17
	v_mul_f32_e32 v23, 0.15915494, v23
	v_add_f32_e32 v7, v58, v59
	v_add_f32_e32 v25, v54, v55
	v_sin_f32_e32 v55, v23
	v_cos_f32_e32 v54, v23
	v_cndmask_b32_e64 v52, v52, v7, s[4:5]
	v_cndmask_b32_e64 v7, v45, v25, s[4:5]
	v_mul_f32_e32 v25, 0x3c23d70b, v21
	v_mul_f32_e32 v23, 0.15915494, v25
	v_sin_f32_e32 v57, v23
	v_cos_f32_e32 v56, v23
	s_waitcnt lgkmcnt(0)
	v_pk_mul_f32 v[58:59], v[54:55], v[30:31]
	s_nop 0
	v_fma_f32 v23, v54, v0, -v59
	v_cndmask_b32_e64 v23, v0, v23, s[2:3]
	v_pk_mul_f32 v[54:55], v[56:57], v[22:23]
	v_add_f32_e32 v0, v58, v59
	v_sub_f32_e32 v25, v54, v55
	v_mov_b32_e32 v54, v57
	v_mov_b32_e32 v55, v56
	v_pk_mul_f32 v[54:55], v[54:55], v[22:23]
	v_cndmask_b32_e64 v30, v30, v0, s[4:5]
	v_add_f32_e32 v27, v54, v55
	v_cndmask_b32_e64 v0, v23, v27, s[4:5]
	v_mul_f32_e32 v23, 0x3b4f3e39, v17
	v_cndmask_b32_e64 v27, v36, v1, s[2:3]
	v_mul_f32_e32 v23, 0.15915494, v23
	ds_bpermute_b32 v37, v13, v27
	v_sin_f32_e32 v55, v23
	v_cos_f32_e32 v54, v23
	v_cndmask_b32_e64 v22, v22, v25, s[4:5]
	v_mul_f32_e32 v25, 0x3b4f3e39, v21
	v_mul_f32_e32 v23, 0.15915494, v25
	v_sin_f32_e32 v57, v23
	v_cos_f32_e32 v56, v23
	s_waitcnt lgkmcnt(0)
	v_pk_mul_f32 v[58:59], v[54:55], v[36:37]
	s_nop 0
	v_fma_f32 v23, v54, v1, -v59
	v_cndmask_b32_e64 v25, v1, v23, s[2:3]
	v_pk_mul_f32 v[54:55], v[56:57], v[24:25]
	v_add_f32_e32 v1, v58, v59
	v_sub_f32_e32 v23, v54, v55
	v_mov_b32_e32 v54, v57
	v_mov_b32_e32 v55, v56
	v_pk_mul_f32 v[54:55], v[54:55], v[24:25]
	v_cndmask_b32_e64 v36, v36, v1, s[4:5]
	v_add_f32_e32 v27, v54, v55
	v_cndmask_b32_e64 v1, v25, v27, s[4:5]
	v_cndmask_b32_e64 v24, v24, v23, s[4:5]
	v_mul_f32_e32 v23, 0x3a831270, v17
	v_cndmask_b32_e64 v27, v42, v2, s[2:3]
	v_mul_f32_e32 v23, 0.15915494, v23
	ds_bpermute_b32 v43, v13, v27
	v_sin_f32_e32 v55, v23
	v_cos_f32_e32 v54, v23
	v_mul_f32_e32 v25, 0x3a831270, v21
	v_mul_f32_e32 v23, 0.15915494, v25
	v_sin_f32_e32 v57, v23
	v_cos_f32_e32 v56, v23
	s_waitcnt lgkmcnt(0)
	v_pk_mul_f32 v[58:59], v[54:55], v[42:43]
	v_mul_f32_e32 v17, 0x39a5cb61, v17
	v_fma_f32 v23, v54, v2, -v59
	v_cndmask_b32_e64 v29, v2, v23, s[2:3]
	v_pk_mul_f32 v[54:55], v[56:57], v[28:29]
	v_mul_f32_e32 v17, 0.15915494, v17
	v_sub_f32_e32 v23, v54, v55
	v_mov_b32_e32 v54, v57
	v_mov_b32_e32 v55, v56
	v_pk_mul_f32 v[54:55], v[54:55], v[28:29]
	v_cndmask_b32_e64 v28, v28, v23, s[4:5]
	v_cndmask_b32_e64 v23, v48, v3, s[2:3]
	ds_bpermute_b32 v49, v13, v23
	v_add_f32_e32 v25, v54, v55
	v_sin_f32_e32 v55, v17
	v_cos_f32_e32 v54, v17
	v_mul_f32_e32 v21, 0x39a5cb61, v21
	v_mul_f32_e32 v17, 0.15915494, v21
	v_sin_f32_e32 v57, v17
	v_cos_f32_e32 v56, v17
	v_add_f32_e32 v2, v58, v59
	s_waitcnt lgkmcnt(0)
	v_pk_mul_f32 v[58:59], v[54:55], v[48:49]
	v_cndmask_b32_e64 v42, v42, v2, s[4:5]
	v_fma_f32 v17, v54, v3, -v59
	v_cndmask_b32_e64 v35, v3, v17, s[2:3]
	v_pk_mul_f32 v[54:55], v[56:57], v[34:35]
	v_add_f32_e32 v3, v58, v59
	v_sub_f32_e32 v17, v54, v55
	v_mov_b32_e32 v54, v57
	v_mov_b32_e32 v55, v56
	v_pk_mul_f32 v[54:55], v[54:55], v[34:35]
	v_cndmask_b32_e64 v2, v29, v25, s[4:5]
	v_add_f32_e32 v21, v54, v55
	v_cndmask_b32_e64 v48, v48, v3, s[4:5]
	v_cndmask_b32_e64 v3, v35, v21, s[4:5]
	v_cndmask_b32_e64 v34, v34, v17, s[4:5]
	s_branch .LBB0_2150
